# attention: removed the full vmcnt(0) drain wave 0 paid before its arithmetic bias (no load targets that register on this path) and relaxed the QK^T prefix wait to vmcnt(5)
# baseline (speedup 1.0000x reference)
.LBB0_976:
	v_subrev_u32_e32 v0, s26, v0
	v_add_u32_e32 v0, 0xffffff00, v0
	v_cvt_f32_i32_e32 v0, v0
	v_mul_f32_e32 v179, v149, v0

.LBB0_986:
	v_add_u32_e32 v64, s88, v200
	v_add_u32_e32 v64, 0xffffff80, v64
	v_cvt_f32_i32_e32 v64, v64
	v_mul_f32_e32 v179, v149, v64
.LBB0_987:
	s_waitcnt vmcnt(5)
	v_add_u32_e32 v76, 0x10900, v157
	ds_read_b128 v[80:83], v76
	ds_read_b128 v[84:87], v76 offset:32
	ds_read_b128 v[64:67], v76 offset:128
	ds_read_b128 v[68:71], v76 offset:160
	ds_read_b128 v[88:91], v76 offset:64
	ds_read_b128 v[72:75], v76 offset:192
	ds_read_b128 v[92:95], v76 offset:96
	ds_read_b128 v[76:79], v76 offset:224
	ds_read_b128 v[222:225], v189 offset:49152
	ds_read_b128 v[226:229], v189 offset:57344
	ds_read_b128 v[240:243], v190 offset:49152
	ds_read_b128 v[244:247], v190 offset:57344
	s_waitcnt lgkmcnt(2)
	v_mfma_f32_32x32x16_bf16 v[80:95], v[222:225], v[96:99], v[80:95]
	v_exp_f32_e32 v172, v172
	v_exp_f32_e32 v173, v173
	v_exp_f32_e32 v170, v170
	v_exp_f32_e32 v171, v171
	v_exp_f32_e32 v168, v168
	v_mfma_f32_32x32x16_bf16 v[64:79], v[226:229], v[96:99], v[64:79]
	ds_read_b128 v[222:225], v191 offset:49152
	ds_read_b128 v[226:229], v191 offset:57344
	v_exp_f32_e32 v169, v169
	v_exp_f32_e32 v203, v166
	v_exp_f32_e32 v206, v167
	v_exp_f32_e32 v238, v158
	v_add_f32_e32 v158, 0, v219
	s_waitcnt lgkmcnt(2)
	v_mfma_f32_32x32x16_bf16 v[64:79], v[244:247], v[100:103], v[64:79]
	v_add_f32_e32 v158, v221, v158
	v_add_f32_e32 v158, v217, v158
	v_add_f32_e32 v158, v220, v158
	v_add_f32_e32 v158, v216, v158
	v_add_f32_e32 v158, v218, v158
	v_mfma_f32_32x32x16_bf16 v[80:95], v[240:243], v[100:103], v[80:95]
	ds_read_b128 v[240:243], v192 offset:49152
	ds_read_b128 v[244:247], v192 offset:57344
	v_add_f32_e32 v158, v214, v158
	v_add_f32_e32 v158, v215, v158
	v_add_f32_e32 v158, v211, v158
	v_add_f32_e32 v158, v213, v158
	v_add_f32_e32 v158, v210, v158
	s_waitcnt lgkmcnt(2)
	v_mfma_f32_32x32x16_bf16 v[64:79], v[226:229], v[104:107], v[64:79]
	v_add_f32_e32 v158, v212, v158
	v_add_f32_e32 v158, v207, v158
	v_add_f32_e32 v158, v209, v158
	v_add_f32_e32 v158, v205, v158
	v_add_f32_e32 v158, v208, v158
	v_mfma_f32_32x32x16_bf16 v[80:95], v[222:225], v[104:107], v[80:95]
	ds_read_b128 v[222:225], v248 offset:49152
	ds_read_b128 v[226:229], v248 offset:57344
	v_add_f32_e32 v158, v172, v158
	v_add_f32_e32 v158, v173, v158
	v_add_f32_e32 v158, v170, v158
	v_add_f32_e32 v158, v171, v158
	v_exp_f32_e32 v232, v164
	s_waitcnt lgkmcnt(2)
	v_mfma_f32_32x32x16_bf16 v[64:79], v[244:247], v[108:111], v[64:79]
	v_add_f32_e32 v158, v168, v158
	v_exp_f32_e32 v233, v165
	v_add_f32_e32 v158, v169, v158
	v_exp_f32_e32 v234, v162
	v_add_f32_e32 v158, v203, v158
	v_mfma_f32_32x32x16_bf16 v[80:95], v[240:243], v[108:111], v[80:95]
	ds_read_b128 v[240:243], v249 offset:49152
	ds_read_b128 v[244:247], v249 offset:57344
	v_exp_f32_e32 v235, v163
	v_add_f32_e32 v158, v206, v158
	v_exp_f32_e32 v236, v160
	v_add_f32_e32 v158, v232, v158
	v_exp_f32_e32 v237, v161
	s_waitcnt lgkmcnt(2)
	v_mfma_f32_32x32x16_bf16 v[64:79], v[226:229], v[112:115], v[64:79]
	v_add_f32_e32 v158, v233, v158
	v_add_f32_e32 v158, v234, v158
	v_exp_f32_e32 v239, v159
	v_add_f32_e32 v158, v235, v158
	v_add_f32_e32 v158, v236, v158
	v_mfma_f32_32x32x16_bf16 v[80:95], v[222:225], v[112:115], v[80:95]
	ds_read_b128 v[222:225], v250 offset:49152
	ds_read_b128 v[226:229], v250 offset:57344
	v_add_f32_e32 v158, v237, v158
	v_add_f32_e32 v158, v238, v158
	v_add_f32_e32 v201, v239, v158
	v_mov_b32_e32 v202, v201
	s_nop 1
	s_waitcnt lgkmcnt(2)
	v_mfma_f32_32x32x16_bf16 v[64:79], v[244:247], v[116:119], v[64:79]
	v_permlane32_swap_b32_e32 v201, v202
	v_cvt_pk_bf16_f32 v158, v219, v221
	v_cvt_pk_bf16_f32 v159, v217, v220
	v_cvt_pk_bf16_f32 v160, v216, v218
	v_cvt_pk_bf16_f32 v161, v214, v215
	v_mfma_f32_32x32x16_bf16 v[80:95], v[240:243], v[116:119], v[80:95]
	ds_read_b128 v[240:243], v251 offset:49152
	ds_read_b128 v[244:247], v251 offset:57344
	v_cvt_pk_bf16_f32 v162, v211, v213
	v_cvt_pk_bf16_f32 v163, v210, v212
	v_cvt_pk_bf16_f32 v164, v207, v209
	v_cvt_pk_bf16_f32 v165, v205, v208
	v_cvt_pk_bf16_f32 v166, v172, v173
	s_waitcnt lgkmcnt(2)
	v_mfma_f32_32x32x16_bf16 v[64:79], v[226:229], v[120:123], v[64:79]
	v_cvt_pk_bf16_f32 v167, v170, v171
	v_cvt_pk_bf16_f32 v168, v168, v169
	v_cvt_pk_bf16_f32 v169, v203, v206
	v_cvt_pk_bf16_f32 v170, v232, v233
	v_cvt_pk_bf16_f32 v171, v234, v235
	v_mfma_f32_32x32x16_bf16 v[80:95], v[222:225], v[120:123], v[80:95]
	v_cvt_pk_bf16_f32 v172, v236, v237
	v_cvt_pk_bf16_f32 v173, v238, v239
	s_nop 0
	v_permlane32_swap_b32_e32 v158, v160
	v_permlane32_swap_b32_e32 v159, v161
	s_waitcnt lgkmcnt(0)
	v_mfma_f32_32x32x16_bf16 v[64:79], v[244:247], v[124:127], v[64:79]
	v_permlane32_swap_b32_e32 v162, v164
	v_permlane32_swap_b32_e32 v163, v165
	v_permlane32_swap_b32_e32 v166, v168
	v_permlane32_swap_b32_e32 v167, v169
	v_permlane32_swap_b32_e32 v170, v172
	v_mfma_f32_32x32x16_bf16 v[80:95], v[240:243], v[124:127], v[80:95]
	v_permlane32_swap_b32_e32 v171, v173
	s_setprio 1
	ds_read_b64_tr_b16 v[206:207], v180 offset:0
	ds_read_b64_tr_b16 v[208:209], v180 offset:0x800
	ds_read_b64_tr_b16 v[210:211], v180 offset:0x1000
	ds_read_b64_tr_b16 v[212:213], v180 offset:0x1800
	ds_read_b64_tr_b16 v[214:215], v180 offset:0x2000
	ds_read_b64_tr_b16 v[216:217], v180 offset:0x2800
	ds_read_b64_tr_b16 v[218:219], v180 offset:0x3000
	ds_read_b64_tr_b16 v[220:221], v180 offset:0x3800
	s_waitcnt lgkmcnt(0)
	s_nop 0
	v_mfma_f32_32x32x16_bf16 v[48:63], v[158:161], v[206:209], v[48:63]
	ds_read_b64_tr_b16 v[206:207], v180 offset:0x200
	ds_read_b64_tr_b16 v[208:209], v180 offset:0xa00
	v_mfma_f32_32x32x16_bf16 v[48:63], v[162:165], v[210:213], v[48:63]
	ds_read_b64_tr_b16 v[210:211], v180 offset:0x1200
	ds_read_b64_tr_b16 v[212:213], v180 offset:0x1a00
	v_mfma_f32_32x32x16_bf16 v[48:63], v[166:169], v[214:217], v[48:63]
	ds_read_b64_tr_b16 v[214:215], v180 offset:0x2200
	ds_read_b64_tr_b16 v[216:217], v180 offset:0x2a00
	ds_read_b64_tr_b16 v[222:223], v180 offset:0x3200
	ds_read_b64_tr_b16 v[224:225], v180 offset:0x3a00
	s_waitcnt lgkmcnt(0)
	v_mfma_f32_32x32x16_bf16 v[48:63], v[170:173], v[218:221], v[48:63]
	v_mfma_f32_32x32x16_bf16 v[32:47], v[158:161], v[206:209], v[32:47]
	ds_read_b64_tr_b16 v[206:207], v180 offset:0x400
	ds_read_b64_tr_b16 v[208:209], v180 offset:0xc00
	v_mfma_f32_32x32x16_bf16 v[32:47], v[162:165], v[210:213], v[32:47]
	ds_read_b64_tr_b16 v[210:211], v180 offset:0x1400
	ds_read_b64_tr_b16 v[212:213], v180 offset:0x1c00
	v_mfma_f32_32x32x16_bf16 v[32:47], v[166:169], v[214:217], v[32:47]
	ds_read_b64_tr_b16 v[214:215], v180 offset:0x2400
	ds_read_b64_tr_b16 v[216:217], v180 offset:0x2c00
	ds_read_b64_tr_b16 v[218:219], v180 offset:0x3400
	ds_read_b64_tr_b16 v[220:221], v180 offset:0x3c00
	s_waitcnt lgkmcnt(0)
	v_mfma_f32_32x32x16_bf16 v[32:47], v[170:173], v[222:225], v[32:47]
	v_mfma_f32_32x32x16_bf16 v[16:31], v[158:161], v[206:209], v[16:31]
	ds_read_b64_tr_b16 v[206:207], v180 offset:0x600
	ds_read_b64_tr_b16 v[208:209], v180 offset:0xe00
	v_mfma_f32_32x32x16_bf16 v[16:31], v[162:165], v[210:213], v[16:31]
	ds_read_b64_tr_b16 v[210:211], v180 offset:0x1600
	ds_read_b64_tr_b16 v[212:213], v180 offset:0x1e00
	v_mfma_f32_32x32x16_bf16 v[16:31], v[166:169], v[214:217], v[16:31]
	ds_read_b64_tr_b16 v[214:215], v180 offset:0x2600
	ds_read_b64_tr_b16 v[216:217], v180 offset:0x2e00
	ds_read_b64_tr_b16 v[222:223], v180 offset:0x3600
	ds_read_b64_tr_b16 v[224:225], v180 offset:0x3e00
	s_waitcnt lgkmcnt(0)
	v_mfma_f32_32x32x16_bf16 v[16:31], v[170:173], v[218:221], v[16:31]
	v_mfma_f32_32x32x16_bf16 v[0:15], v[158:161], v[206:209], v[0:15]
	v_mfma_f32_32x32x16_bf16 v[0:15], v[162:165], v[210:213], v[0:15]
	v_mfma_f32_32x32x16_bf16 v[0:15], v[166:169], v[214:217], v[0:15]
	v_mfma_f32_32x32x16_bf16 v[0:15], v[170:173], v[222:225], v[0:15]
	s_setprio 0
	s_add_i32 s0, s88, 0x7f
	s_cmp_le_i32 s0, s87
	s_cbranch_scc1 .LBB0_989
	v_add_u32_e32 v158, 0x4000007b, v199
	v_cmp_gt_u32_e32 vcc, 2.0, v158
	v_add_u32_e32 v158, 0x5b, v199
	s_nop 0
	v_cndmask_b32_e32 v80, v193, v80, vcc
	v_cmp_lt_u32_e32 vcc, s78, v158
	v_add_u32_e32 v158, 0x7a, v199
	s_nop 0
	v_cndmask_b32_e32 v64, v193, v64, vcc
	v_cmp_lt_u32_e32 vcc, s78, v158
	v_add_u32_e32 v158, 0x5a, v199
	s_nop 0
	v_cndmask_b32_e32 v81, v193, v81, vcc
	v_cmp_lt_u32_e32 vcc, s78, v158
	v_add_u32_e32 v158, 0x79, v199
	s_nop 0
	v_cndmask_b32_e32 v65, v193, v65, vcc
	v_cmp_lt_u32_e32 vcc, s78, v158
	v_add_u32_e32 v158, 0x59, v199
	s_nop 0
	v_cndmask_b32_e32 v82, v193, v82, vcc
	v_cmp_lt_u32_e32 vcc, s78, v158
	v_add_u32_e32 v158, 0x78, v199
	s_nop 0
	v_cndmask_b32_e32 v66, v193, v66, vcc
	v_cmp_lt_u32_e32 vcc, s78, v158
	v_add_u32_e32 v158, 0x58, v199
	s_nop 0
	v_cndmask_b32_e32 v83, v193, v83, vcc
	v_cmp_lt_u32_e32 vcc, s78, v158
	v_add_u32_e32 v158, 0x73, v199
	s_nop 0
	v_cndmask_b32_e32 v67, v193, v67, vcc
	v_cmp_lt_u32_e32 vcc, s78, v158
	v_add_u32_e32 v158, 0x53, v199
	s_nop 0
	v_cndmask_b32_e32 v84, v193, v84, vcc
	v_cmp_lt_u32_e32 vcc, s78, v158
	v_add_u32_e32 v158, 0x72, v199
	s_nop 0
	v_cndmask_b32_e32 v68, v193, v68, vcc
	v_cmp_lt_u32_e32 vcc, s78, v158
	v_add_u32_e32 v158, 0x52, v199
	s_nop 0
	v_cndmask_b32_e32 v85, v193, v85, vcc
	v_cmp_lt_u32_e32 vcc, s78, v158
	v_add_u32_e32 v158, 0x71, v199
	s_nop 0
	v_cndmask_b32_e32 v69, v193, v69, vcc
	v_cmp_lt_u32_e32 vcc, s78, v158
	v_add_u32_e32 v158, 0x51, v199
	s_nop 0
	v_cndmask_b32_e32 v86, v193, v86, vcc
	v_cmp_lt_u32_e32 vcc, s78, v158
	v_add_u32_e32 v158, 0x70, v199
	s_nop 0
	v_cndmask_b32_e32 v70, v193, v70, vcc
	v_cmp_lt_u32_e32 vcc, s78, v158
	v_add_u32_e32 v158, 0x50, v199
	s_nop 0
	v_cndmask_b32_e32 v87, v193, v87, vcc
	v_cmp_lt_u32_e32 vcc, s78, v158
	v_add_u32_e32 v158, 0x6b, v199
	s_nop 0
	v_cndmask_b32_e32 v71, v193, v71, vcc
	v_cmp_lt_u32_e32 vcc, s78, v158
	v_add_u32_e32 v158, 0x4b, v199
	s_nop 0
	v_cndmask_b32_e32 v88, v193, v88, vcc
	v_cmp_lt_u32_e32 vcc, s78, v158
	v_add_u32_e32 v158, 0x6a, v199
	s_nop 0
	v_cndmask_b32_e32 v72, v193, v72, vcc
	v_cmp_lt_u32_e32 vcc, s78, v158
	v_add_u32_e32 v158, 0x4a, v199
	s_nop 0
	v_cndmask_b32_e32 v89, v193, v89, vcc
	v_cmp_lt_u32_e32 vcc, s78, v158
	v_add_u32_e32 v158, 0x69, v199
	s_nop 0
	v_cndmask_b32_e32 v73, v193, v73, vcc
	v_cmp_lt_u32_e32 vcc, s78, v158
	v_add_u32_e32 v158, 0x49, v199
	s_nop 0
	v_cndmask_b32_e32 v90, v193, v90, vcc
	v_cmp_lt_u32_e32 vcc, s78, v158
	v_add_u32_e32 v158, 0x68, v199
	s_nop 0
	v_cndmask_b32_e32 v74, v193, v74, vcc
	v_cmp_lt_u32_e32 vcc, s78, v158
	v_add_u32_e32 v158, 0x48, v199
	s_nop 0
	v_cndmask_b32_e32 v91, v193, v91, vcc
	v_cmp_lt_u32_e32 vcc, s78, v158
	v_add_u32_e32 v158, 0x63, v199
	s_nop 0
	v_cndmask_b32_e32 v75, v193, v75, vcc
	v_cmp_lt_u32_e32 vcc, s78, v158
	v_add_u32_e32 v158, 0x43, v199
	s_nop 0
	v_cndmask_b32_e32 v92, v193, v92, vcc
	v_cmp_lt_u32_e32 vcc, s78, v158
	v_add_u32_e32 v158, 0x62, v199
	s_nop 0
	v_cndmask_b32_e32 v76, v193, v76, vcc
	v_cmp_lt_u32_e32 vcc, s78, v158
	v_add_u32_e32 v158, 0x42, v199
	s_nop 0
	v_cndmask_b32_e32 v93, v193, v93, vcc
	v_cmp_lt_u32_e32 vcc, s78, v158
	v_add_u32_e32 v158, 0x61, v199
	s_nop 0
	v_cndmask_b32_e32 v77, v193, v77, vcc
	v_cmp_lt_u32_e32 vcc, s78, v158
	v_add_u32_e32 v158, 0x41, v199
	s_nop 0
	v_cndmask_b32_e32 v94, v193, v94, vcc
	v_cmp_lt_u32_e32 vcc, s78, v158
	v_add_u32_e32 v158, 0x60, v199
	s_nop 0
	v_cndmask_b32_e32 v78, v193, v78, vcc
	v_cmp_lt_u32_e32 vcc, s78, v158
	v_add_u32_e32 v158, 64, v199
	s_nop 0
	v_cndmask_b32_e32 v95, v193, v95, vcc
	v_cmp_lt_u32_e32 vcc, s78, v158
	s_nop 1
	v_cndmask_b32_e32 v79, v193, v79, vcc

.LBB0_999:
	v_add_u32_e32 v64, s88, v200
	v_subrev_u32_e32 v64, 64, v64
	v_cvt_f32_i32_e32 v64, v64
	v_mul_f32_e32 v179, v149, v64

.LBB0_1018:
	v_subrev_u32_e32 v80, s81, v80
	v_add_u32_e32 v80, 0xffffff00, v80
	v_cvt_f32_i32_e32 v80, v80
	v_mul_f32_e32 v179, v196, v80

.LBB0_1216:
	v_add_u32_e32 v64, s87, v200
	v_add_u32_e32 v64, 0xffffff80, v64
	v_cvt_f32_i32_e32 v64, v64
	v_mul_f32_e32 v179, v149, v64
.LBB0_1217:
	s_waitcnt vmcnt(5)
	v_add_u32_e32 v76, 0x10900, v157
	ds_read_b128 v[80:83], v76
	ds_read_b128 v[84:87], v76 offset:32
	ds_read_b128 v[64:67], v76 offset:128
	ds_read_b128 v[68:71], v76 offset:160
	ds_read_b128 v[88:91], v76 offset:64
	ds_read_b128 v[72:75], v76 offset:192
	ds_read_b128 v[92:95], v76 offset:96
	ds_read_b128 v[76:79], v76 offset:224
	ds_read_b128 v[222:225], v189 offset:49152
	ds_read_b128 v[226:229], v189 offset:57344
	ds_read_b128 v[240:243], v190 offset:49152
	ds_read_b128 v[244:247], v190 offset:57344
	s_waitcnt lgkmcnt(2)
	v_mfma_f32_32x32x16_bf16 v[80:95], v[222:225], v[96:99], v[80:95]
	v_exp_f32_e32 v172, v172
	v_exp_f32_e32 v173, v173
	v_exp_f32_e32 v170, v170
	v_exp_f32_e32 v171, v171
	v_exp_f32_e32 v168, v168
	v_mfma_f32_32x32x16_bf16 v[64:79], v[226:229], v[96:99], v[64:79]
	ds_read_b128 v[222:225], v191 offset:49152
	ds_read_b128 v[226:229], v191 offset:57344
	v_exp_f32_e32 v169, v169
	v_exp_f32_e32 v203, v166
	v_exp_f32_e32 v206, v167
	v_exp_f32_e32 v238, v158
	v_add_f32_e32 v158, 0, v219
	s_waitcnt lgkmcnt(2)
	v_mfma_f32_32x32x16_bf16 v[64:79], v[244:247], v[100:103], v[64:79]
	v_add_f32_e32 v158, v221, v158
	v_add_f32_e32 v158, v217, v158
	v_add_f32_e32 v158, v220, v158
	v_add_f32_e32 v158, v216, v158
	v_add_f32_e32 v158, v218, v158
	v_mfma_f32_32x32x16_bf16 v[80:95], v[240:243], v[100:103], v[80:95]
	ds_read_b128 v[240:243], v192 offset:49152
	ds_read_b128 v[244:247], v192 offset:57344
	v_add_f32_e32 v158, v214, v158
	v_add_f32_e32 v158, v215, v158
	v_add_f32_e32 v158, v211, v158
	v_add_f32_e32 v158, v213, v158
	v_add_f32_e32 v158, v210, v158
	s_waitcnt lgkmcnt(2)
	v_mfma_f32_32x32x16_bf16 v[64:79], v[226:229], v[104:107], v[64:79]
	v_add_f32_e32 v158, v212, v158
	v_add_f32_e32 v158, v207, v158
	v_add_f32_e32 v158, v209, v158
	v_add_f32_e32 v158, v205, v158
	v_add_f32_e32 v158, v208, v158
	v_mfma_f32_32x32x16_bf16 v[80:95], v[222:225], v[104:107], v[80:95]
	ds_read_b128 v[222:225], v248 offset:49152
	ds_read_b128 v[226:229], v248 offset:57344
	v_add_f32_e32 v158, v172, v158
	v_add_f32_e32 v158, v173, v158
	v_add_f32_e32 v158, v170, v158
	v_add_f32_e32 v158, v171, v158
	v_exp_f32_e32 v232, v164
	s_waitcnt lgkmcnt(2)
	v_mfma_f32_32x32x16_bf16 v[64:79], v[244:247], v[108:111], v[64:79]
	v_add_f32_e32 v158, v168, v158
	v_exp_f32_e32 v233, v165
	v_add_f32_e32 v158, v169, v158
	v_exp_f32_e32 v234, v162
	v_add_f32_e32 v158, v203, v158
	v_mfma_f32_32x32x16_bf16 v[80:95], v[240:243], v[108:111], v[80:95]
	ds_read_b128 v[240:243], v249 offset:49152
	ds_read_b128 v[244:247], v249 offset:57344
	v_exp_f32_e32 v235, v163
	v_add_f32_e32 v158, v206, v158
	v_exp_f32_e32 v236, v160
	v_add_f32_e32 v158, v232, v158
	v_exp_f32_e32 v237, v161
	s_waitcnt lgkmcnt(2)
	v_mfma_f32_32x32x16_bf16 v[64:79], v[226:229], v[112:115], v[64:79]
	v_add_f32_e32 v158, v233, v158
	v_add_f32_e32 v158, v234, v158
	v_exp_f32_e32 v239, v159
	v_add_f32_e32 v158, v235, v158
	v_add_f32_e32 v158, v236, v158
	v_mfma_f32_32x32x16_bf16 v[80:95], v[222:225], v[112:115], v[80:95]
	ds_read_b128 v[222:225], v250 offset:49152
	ds_read_b128 v[226:229], v250 offset:57344
	v_add_f32_e32 v158, v237, v158
	v_add_f32_e32 v158, v238, v158
	v_add_f32_e32 v201, v239, v158
	v_mov_b32_e32 v202, v201
	s_nop 1
	s_waitcnt lgkmcnt(2)
	v_mfma_f32_32x32x16_bf16 v[64:79], v[244:247], v[116:119], v[64:79]
	v_permlane32_swap_b32_e32 v201, v202
	v_cvt_pk_bf16_f32 v158, v219, v221
	v_cvt_pk_bf16_f32 v159, v217, v220
	v_cvt_pk_bf16_f32 v160, v216, v218
	v_cvt_pk_bf16_f32 v161, v214, v215
	v_mfma_f32_32x32x16_bf16 v[80:95], v[240:243], v[116:119], v[80:95]
	ds_read_b128 v[240:243], v251 offset:49152
	ds_read_b128 v[244:247], v251 offset:57344
	v_cvt_pk_bf16_f32 v162, v211, v213
	v_cvt_pk_bf16_f32 v163, v210, v212
	v_cvt_pk_bf16_f32 v164, v207, v209
	v_cvt_pk_bf16_f32 v165, v205, v208
	v_cvt_pk_bf16_f32 v166, v172, v173
	s_waitcnt lgkmcnt(2)
	v_mfma_f32_32x32x16_bf16 v[64:79], v[226:229], v[120:123], v[64:79]
	v_cvt_pk_bf16_f32 v167, v170, v171
	v_cvt_pk_bf16_f32 v168, v168, v169
	v_cvt_pk_bf16_f32 v169, v203, v206
	v_cvt_pk_bf16_f32 v170, v232, v233
	v_cvt_pk_bf16_f32 v171, v234, v235
	v_mfma_f32_32x32x16_bf16 v[80:95], v[222:225], v[120:123], v[80:95]
	v_cvt_pk_bf16_f32 v172, v236, v237
	v_cvt_pk_bf16_f32 v173, v238, v239
	s_nop 0
	v_permlane32_swap_b32_e32 v158, v160
	v_permlane32_swap_b32_e32 v159, v161
	s_waitcnt lgkmcnt(0)
	v_mfma_f32_32x32x16_bf16 v[64:79], v[244:247], v[124:127], v[64:79]
	v_permlane32_swap_b32_e32 v162, v164
	v_permlane32_swap_b32_e32 v163, v165
	v_permlane32_swap_b32_e32 v166, v168
	v_permlane32_swap_b32_e32 v167, v169
	v_permlane32_swap_b32_e32 v170, v172
	v_mfma_f32_32x32x16_bf16 v[80:95], v[240:243], v[124:127], v[80:95]
	v_permlane32_swap_b32_e32 v171, v173
	s_setprio 1
	ds_read_b64_tr_b16 v[206:207], v180 offset:0
	ds_read_b64_tr_b16 v[208:209], v180 offset:0x800
	ds_read_b64_tr_b16 v[210:211], v180 offset:0x1000
	ds_read_b64_tr_b16 v[212:213], v180 offset:0x1800
	ds_read_b64_tr_b16 v[214:215], v180 offset:0x2000
	ds_read_b64_tr_b16 v[216:217], v180 offset:0x2800
	ds_read_b64_tr_b16 v[218:219], v180 offset:0x3000
	ds_read_b64_tr_b16 v[220:221], v180 offset:0x3800
	s_waitcnt lgkmcnt(0)
	s_nop 0
	v_mfma_f32_32x32x16_bf16 v[48:63], v[158:161], v[206:209], v[48:63]
	ds_read_b64_tr_b16 v[206:207], v180 offset:0x200
	ds_read_b64_tr_b16 v[208:209], v180 offset:0xa00
	v_mfma_f32_32x32x16_bf16 v[48:63], v[162:165], v[210:213], v[48:63]
	ds_read_b64_tr_b16 v[210:211], v180 offset:0x1200
	ds_read_b64_tr_b16 v[212:213], v180 offset:0x1a00
	v_mfma_f32_32x32x16_bf16 v[48:63], v[166:169], v[214:217], v[48:63]
	ds_read_b64_tr_b16 v[214:215], v180 offset:0x2200
	ds_read_b64_tr_b16 v[216:217], v180 offset:0x2a00
	ds_read_b64_tr_b16 v[222:223], v180 offset:0x3200
	ds_read_b64_tr_b16 v[224:225], v180 offset:0x3a00
	s_waitcnt lgkmcnt(0)
	v_mfma_f32_32x32x16_bf16 v[48:63], v[170:173], v[218:221], v[48:63]
	v_mfma_f32_32x32x16_bf16 v[32:47], v[158:161], v[206:209], v[32:47]
	ds_read_b64_tr_b16 v[206:207], v180 offset:0x400
	ds_read_b64_tr_b16 v[208:209], v180 offset:0xc00
	v_mfma_f32_32x32x16_bf16 v[32:47], v[162:165], v[210:213], v[32:47]
	ds_read_b64_tr_b16 v[210:211], v180 offset:0x1400
	ds_read_b64_tr_b16 v[212:213], v180 offset:0x1c00
	v_mfma_f32_32x32x16_bf16 v[32:47], v[166:169], v[214:217], v[32:47]
	ds_read_b64_tr_b16 v[214:215], v180 offset:0x2400
	ds_read_b64_tr_b16 v[216:217], v180 offset:0x2c00
	ds_read_b64_tr_b16 v[218:219], v180 offset:0x3400
	ds_read_b64_tr_b16 v[220:221], v180 offset:0x3c00
	s_waitcnt lgkmcnt(0)
	v_mfma_f32_32x32x16_bf16 v[32:47], v[170:173], v[222:225], v[32:47]
	v_mfma_f32_32x32x16_bf16 v[16:31], v[158:161], v[206:209], v[16:31]
	ds_read_b64_tr_b16 v[206:207], v180 offset:0x600
	ds_read_b64_tr_b16 v[208:209], v180 offset:0xe00
	v_mfma_f32_32x32x16_bf16 v[16:31], v[162:165], v[210:213], v[16:31]
	ds_read_b64_tr_b16 v[210:211], v180 offset:0x1600
	ds_read_b64_tr_b16 v[212:213], v180 offset:0x1e00
	v_mfma_f32_32x32x16_bf16 v[16:31], v[166:169], v[214:217], v[16:31]
	ds_read_b64_tr_b16 v[214:215], v180 offset:0x2600
	ds_read_b64_tr_b16 v[216:217], v180 offset:0x2e00
	ds_read_b64_tr_b16 v[222:223], v180 offset:0x3600
	ds_read_b64_tr_b16 v[224:225], v180 offset:0x3e00
	s_waitcnt lgkmcnt(0)
	v_mfma_f32_32x32x16_bf16 v[16:31], v[170:173], v[218:221], v[16:31]
	v_mfma_f32_32x32x16_bf16 v[0:15], v[158:161], v[206:209], v[0:15]
	v_mfma_f32_32x32x16_bf16 v[0:15], v[162:165], v[210:213], v[0:15]
	v_mfma_f32_32x32x16_bf16 v[0:15], v[166:169], v[214:217], v[0:15]
	v_mfma_f32_32x32x16_bf16 v[0:15], v[170:173], v[222:225], v[0:15]
	s_setprio 0
	s_add_i32 s0, s87, 0x7f
	s_cmp_le_i32 s0, s86
	s_cbranch_scc1 .LBB0_1219
	v_add_u32_e32 v158, 0x4000007b, v199
	v_cmp_gt_u32_e32 vcc, 2.0, v158
	v_add_u32_e32 v158, 0x5b, v199
	s_nop 0
	v_cndmask_b32_e32 v80, v193, v80, vcc
	v_cmp_lt_u32_e32 vcc, s77, v158
	v_add_u32_e32 v158, 0x7a, v199
	s_nop 0
	v_cndmask_b32_e32 v64, v193, v64, vcc
	v_cmp_lt_u32_e32 vcc, s77, v158
	v_add_u32_e32 v158, 0x5a, v199
	s_nop 0
	v_cndmask_b32_e32 v81, v193, v81, vcc
	v_cmp_lt_u32_e32 vcc, s77, v158
	v_add_u32_e32 v158, 0x79, v199
	s_nop 0
	v_cndmask_b32_e32 v65, v193, v65, vcc
	v_cmp_lt_u32_e32 vcc, s77, v158
	v_add_u32_e32 v158, 0x59, v199
	s_nop 0
	v_cndmask_b32_e32 v82, v193, v82, vcc
	v_cmp_lt_u32_e32 vcc, s77, v158
	v_add_u32_e32 v158, 0x78, v199
	s_nop 0
	v_cndmask_b32_e32 v66, v193, v66, vcc
	v_cmp_lt_u32_e32 vcc, s77, v158
	v_add_u32_e32 v158, 0x58, v199
	s_nop 0
	v_cndmask_b32_e32 v83, v193, v83, vcc
	v_cmp_lt_u32_e32 vcc, s77, v158
	v_add_u32_e32 v158, 0x73, v199
	s_nop 0
	v_cndmask_b32_e32 v67, v193, v67, vcc
	v_cmp_lt_u32_e32 vcc, s77, v158
	v_add_u32_e32 v158, 0x53, v199
	s_nop 0
	v_cndmask_b32_e32 v84, v193, v84, vcc
	v_cmp_lt_u32_e32 vcc, s77, v158
	v_add_u32_e32 v158, 0x72, v199
	s_nop 0
	v_cndmask_b32_e32 v68, v193, v68, vcc
	v_cmp_lt_u32_e32 vcc, s77, v158
	v_add_u32_e32 v158, 0x52, v199
	s_nop 0
	v_cndmask_b32_e32 v85, v193, v85, vcc
	v_cmp_lt_u32_e32 vcc, s77, v158
	v_add_u32_e32 v158, 0x71, v199
	s_nop 0
	v_cndmask_b32_e32 v69, v193, v69, vcc
	v_cmp_lt_u32_e32 vcc, s77, v158
	v_add_u32_e32 v158, 0x51, v199
	s_nop 0
	v_cndmask_b32_e32 v86, v193, v86, vcc
	v_cmp_lt_u32_e32 vcc, s77, v158
	v_add_u32_e32 v158, 0x70, v199
	s_nop 0
	v_cndmask_b32_e32 v70, v193, v70, vcc
	v_cmp_lt_u32_e32 vcc, s77, v158
	v_add_u32_e32 v158, 0x50, v199
	s_nop 0
	v_cndmask_b32_e32 v87, v193, v87, vcc
	v_cmp_lt_u32_e32 vcc, s77, v158
	v_add_u32_e32 v158, 0x6b, v199
	s_nop 0
	v_cndmask_b32_e32 v71, v193, v71, vcc
	v_cmp_lt_u32_e32 vcc, s77, v158
	v_add_u32_e32 v158, 0x4b, v199
	s_nop 0
	v_cndmask_b32_e32 v88, v193, v88, vcc
	v_cmp_lt_u32_e32 vcc, s77, v158
	v_add_u32_e32 v158, 0x6a, v199
	s_nop 0
	v_cndmask_b32_e32 v72, v193, v72, vcc
	v_cmp_lt_u32_e32 vcc, s77, v158
	v_add_u32_e32 v158, 0x4a, v199
	s_nop 0
	v_cndmask_b32_e32 v89, v193, v89, vcc
	v_cmp_lt_u32_e32 vcc, s77, v158
	v_add_u32_e32 v158, 0x69, v199
	s_nop 0
	v_cndmask_b32_e32 v73, v193, v73, vcc
	v_cmp_lt_u32_e32 vcc, s77, v158
	v_add_u32_e32 v158, 0x49, v199
	s_nop 0
	v_cndmask_b32_e32 v90, v193, v90, vcc
	v_cmp_lt_u32_e32 vcc, s77, v158
	v_add_u32_e32 v158, 0x68, v199
	s_nop 0
	v_cndmask_b32_e32 v74, v193, v74, vcc
	v_cmp_lt_u32_e32 vcc, s77, v158
	v_add_u32_e32 v158, 0x48, v199
	s_nop 0
	v_cndmask_b32_e32 v91, v193, v91, vcc
	v_cmp_lt_u32_e32 vcc, s77, v158
	v_add_u32_e32 v158, 0x63, v199
	s_nop 0
	v_cndmask_b32_e32 v75, v193, v75, vcc
	v_cmp_lt_u32_e32 vcc, s77, v158
	v_add_u32_e32 v158, 0x43, v199
	s_nop 0
	v_cndmask_b32_e32 v92, v193, v92, vcc
	v_cmp_lt_u32_e32 vcc, s77, v158
	v_add_u32_e32 v158, 0x62, v199
	s_nop 0
	v_cndmask_b32_e32 v76, v193, v76, vcc
	v_cmp_lt_u32_e32 vcc, s77, v158
	v_add_u32_e32 v158, 0x42, v199
	s_nop 0
	v_cndmask_b32_e32 v93, v193, v93, vcc
	v_cmp_lt_u32_e32 vcc, s77, v158
	v_add_u32_e32 v158, 0x61, v199
	s_nop 0
	v_cndmask_b32_e32 v77, v193, v77, vcc
	v_cmp_lt_u32_e32 vcc, s77, v158
	v_add_u32_e32 v158, 0x41, v199
	s_nop 0
	v_cndmask_b32_e32 v94, v193, v94, vcc
	v_cmp_lt_u32_e32 vcc, s77, v158
	v_add_u32_e32 v158, 0x60, v199
	s_nop 0
	v_cndmask_b32_e32 v78, v193, v78, vcc
	v_cmp_lt_u32_e32 vcc, s77, v158
	v_add_u32_e32 v158, 64, v199
	s_nop 0
	v_cndmask_b32_e32 v95, v193, v95, vcc
	v_cmp_lt_u32_e32 vcc, s77, v158
	s_nop 1
	v_cndmask_b32_e32 v79, v193, v79, vcc

.LBB0_1229:
	v_add_u32_e32 v64, s87, v200
	v_subrev_u32_e32 v64, 64, v64
	v_cvt_f32_i32_e32 v64, v64
	v_mul_f32_e32 v179, v149, v64

.LBB0_1248:
	v_subrev_u32_e32 v80, s80, v80
	v_add_u32_e32 v80, 0xffffff00, v80
	v_cvt_f32_i32_e32 v80, v80
	v_mul_f32_e32 v179, v196, v80
